# residual GEMM epilogue: next group of residual-row loads issued while the current group is processed (on top of v32)
# speedup vs baseline: 1.0030x; 1.0030x over previous
; __device__ __forceinline__ unsigned cvt_pk(float lo, float hi) { f32x2_t v = {lo, hi}; bf16x2_t b = __builtin_convertvector(v, bf16x2_t); return __builtin_bit_cast(unsigned, b); }
; __device__ __forceinline__ void epi_resid(Acc& acc, int pm, int pn, const float* xsrc, float* xdst, bf16_t* xb, float* ssq, float alpha, LAS unsigned char* lds) {
;     ...
;             f32x4 xs[2][2][2];
; #pragma unroll
;             for (int mm = 0; mm < 2; ++mm)
; #pragma unroll
;                 for (int bj = 0; bj < 2; ++bj)
; #pragma unroll
;                     for (int n = 0; n < 2; ++n) {
;                         const int row = pm * 256 + ai * 128 + t.wr * 64 + (mp * 2 + mm) * 16 + t.fr;
;                         xs[mm][bj][n] = *(const f32x4*)(xsrc + (size_t)row * DM + pn * 256 + bj * 128 + t.wc * 32 + n * 16 + t.fq * 4);
;                     }
; #pragma unroll
;             for (int mm = 0; mm < 2; ++mm) {
;                 const int m = mp * 2 + mm;
;                 const int rl = ai * 128 + t.wr * 64 + m * 16 + t.fr;
;                 const int row = pm * 256 + rl;
;                 float ss = 0.f;
; #pragma unroll
;                 for (int bj = 0; bj < 2; ++bj)
; #pragma unroll
;                     for (int n = 0; n < 2; ++n) {
;                         size_t off = (size_t)row * DM + pn * 256 + bj * 128 + t.wc * 32 + n * 16 + t.fq * 4;
;                         f32x4 v = xs[mm][bj][n] + acc[ai][bj][m][n] * alpha;
;                         *(f32x4*)(xdst + off) = v;
;                         u32x2 w; w[0] = cvt_pk(v[0], v[1]); w[1] = cvt_pk(v[2], v[3]);
;                         *(u32x2*)(xb + off) = w;
;                         ss += v[0] * v[0] + v[1] * v[1] + v[2] * v[2] + v[3] * v[3];
;                     }
;                 ss += __shfl_xor(ss, 16); ss += __shfl_xor(ss, 32);
;                 if (t.fq == 0) red[t.wc * 256 + rl] = ss;
.LBB0_100:
	s_or_b64 exec, exec, s[40:41]
	s_waitcnt vmcnt(0)
	s_barrier
	v_mov_b32 v1, v179
	s_lshl_b64 s[40:41], s[36:37], 2
	v_and_b32_e32 v121, 15, v1
	v_ashrrev_i32_e32 v118, 2, v1
	v_bfe_u32 v120, v1, 6, 2
	v_and_b32_e32 v123, 0xffffffc0, v118
	v_or_b32_e32 v118, s13, v121
	v_bfe_u32 v122, v1, 4, 2
	v_add_u32_e32 v156, v118, v123
	v_lshl_add_u64 v[118:119], v[142:143], 0, s[40:41]
	v_lshlrev_b32_e32 v144, 7, v120
	v_lshl_add_u64 v[118:119], v[118:119], 0, v[144:145]
	v_lshlrev_b32_e32 v144, 4, v122
	v_lshl_add_u64 v[158:159], v[118:119], 0, v[144:145]
	v_and_b32_e32 v119, 64, v195
	v_xor_b32_e32 v118, 16, v195
	v_add_u32_e32 v119, 64, v119
	v_cmp_lt_i32_e32 vcc, v118, v119
	v_ashrrev_i32_e32 v157, 31, v156
	v_lshlrev_b32_e32 v124, 5, v120
	v_cndmask_b32_e32 v118, v195, v118, vcc
	v_lshlrev_b32_e32 v162, 2, v118
	v_xor_b32_e32 v118, 32, v195
	v_cmp_lt_i32_e32 vcc, v118, v119
	v_lshlrev_b32_e32 v125, 2, v122
	v_or_b32_e32 v163, v123, v121
	v_cndmask_b32_e32 v118, v195, v118, vcc
	v_lshlrev_b32_e32 v144, 2, v118
	v_lshlrev_b64 v[118:119], 12, v[156:157]
	v_lshl_add_u64 v[118:119], v[158:159], 0, v[118:119]
	flat_load_dwordx4 v[166:169], v[118:119]
	flat_load_dwordx4 v[170:173], v[118:119] offset:64
	flat_load_dwordx4 v[174:177], v[118:119] offset:512
	flat_load_dwordx4 v[134:137], v[118:119] offset:576
	v_or_b32_e32 v118, 16, v156
	v_ashrrev_i32_e32 v119, 31, v118
	v_lshlrev_b64 v[118:119], 12, v[118:119]
	v_lshl_add_u64 v[118:119], v[158:159], 0, v[118:119]
	v_or3_b32 v154, s36, v124, v125
	v_mov_b32_e32 v155, s37
	v_cmp_eq_u32_e64 s[36:37], 0, v122
	v_lshl_add_u32 v164, v120, 10, 0
	flat_load_dwordx4 v[130:133], v[118:119]
	flat_load_dwordx4 v[126:129], v[118:119] offset:64
	flat_load_dwordx4 v[122:125], v[118:119] offset:512
	s_nop 0
	flat_load_dwordx4 v[118:121], v[118:119] offset:576
	v_add_u32_e32 v188, 0x20, v156
	v_ashrrev_i32_e32 v189, 31, v188
	v_lshlrev_b64 v[188:189], 12, v[188:189]
	v_lshl_add_u64 v[188:189], v[158:159], 0, v[188:189]
	global_load_dwordx4 v[204:207], v[188:189], off
	global_load_dwordx4 v[208:211], v[188:189], off offset:64
	global_load_dwordx4 v[212:215], v[188:189], off offset:512
	global_load_dwordx4 v[216:219], v[188:189], off offset:576
	v_add_u32_e32 v190, 0x30, v156
	v_ashrrev_i32_e32 v191, 31, v190
	v_lshlrev_b64 v[190:191], 12, v[190:191]
	v_lshl_add_u64 v[190:191], v[158:159], 0, v[190:191]
	global_load_dwordx4 v[220:223], v[190:191], off
	global_load_dwordx4 v[224:227], v[190:191], off offset:64
	global_load_dwordx4 v[228:231], v[190:191], off offset:512
	global_load_dwordx4 v[232:235], v[190:191], off offset:576
	v_add_u32_e32 v160, s13, v163
	v_ashrrev_i32_e32 v161, 31, v160
	v_lshlrev_b64 v[184:185], 10, v[160:161]
	v_lshl_add_u64 v[184:185], v[184:185], 0, v[154:155]
	v_mov_b32_e32 v181, v180
	s_waitcnt vmcnt(0) lgkmcnt(0)
	v_pk_fma_f32 v[168:169], v[180:181], v[152:153], v[168:169]
	v_pk_fma_f32 v[166:167], v[182:183], v[150:151], v[166:167]
	v_lshlrev_b64 v[152:153], 1, v[184:185]
	v_lshl_add_u64 v[150:151], v[184:185], 2, s[20:21]
	v_cvt_pk_bf16_f32 v186, v166, v167
	v_cvt_pk_bf16_f32 v187, v168, v169
	v_lshl_add_u64 v[184:185], s[34:35], 0, v[152:153]
	v_mul_f32_e32 v161, v167, v167
	v_pk_fma_f32 v[148:149], v[180:181], v[148:149], v[172:173]
	v_pk_fma_f32 v[146:147], v[182:183], v[146:147], v[170:171]
	global_store_dwordx4 v[150:151], v[166:169], off
	global_store_dwordx2 v[184:185], v[186:187], off
	v_fmac_f32_e32 v161, v166, v166
	global_store_dwordx4 v[150:151], v[146:149], off offset:64
	v_cvt_pk_bf16_f32 v166, v146, v147
	v_fmac_f32_e32 v161, v168, v168
	v_mul_f32_e32 v147, v147, v147
	v_fmac_f32_e32 v147, v146, v146
	v_fmac_f32_e32 v161, v169, v169
	v_or_b32_e32 v168, 32, v152
	v_mov_b32_e32 v169, v153
	v_fmac_f32_e32 v147, v148, v148
	v_cvt_pk_bf16_f32 v167, v148, v149
	v_lshl_add_u64 v[168:169], s[34:35], 0, v[168:169]
	v_fmac_f32_e32 v147, v149, v149
	v_pk_fma_f32 v[140:141], v[180:181], v[140:141], v[176:177]
	v_pk_fma_f32 v[138:139], v[182:183], v[138:139], v[174:175]
	v_or_b32_e32 v148, 0x100, v152
	v_mov_b32_e32 v149, v153
	global_store_dwordx2 v[168:169], v[166:167], off
	v_add_f32_e32 v161, v161, v147
	global_store_dwordx4 v[150:151], v[138:141], off offset:512
	v_cvt_pk_bf16_f32 v146, v138, v139
	v_cvt_pk_bf16_f32 v147, v140, v141
	v_lshl_add_u64 v[148:149], s[34:35], 0, v[148:149]
	v_mul_f32_e32 v139, v139, v139
	v_pk_fma_f32 v[116:117], v[180:181], v[116:117], v[136:137]
	v_pk_fma_f32 v[114:115], v[182:183], v[114:115], v[134:135]
	global_store_dwordx2 v[148:149], v[146:147], off
	v_fmac_f32_e32 v139, v138, v138
	global_store_dwordx4 v[150:151], v[114:117], off offset:576
	v_cvt_pk_bf16_f32 v134, v114, v115
	v_fmac_f32_e32 v139, v140, v140
	v_mul_f32_e32 v115, v115, v115
	v_fmac_f32_e32 v115, v114, v114
	v_fmac_f32_e32 v139, v141, v141
	v_fmac_f32_e32 v115, v116, v116
	v_add_f32_e32 v138, v161, v139
	v_fmac_f32_e32 v115, v117, v117
	v_add_f32_e32 v114, v138, v115
	ds_bpermute_b32 v115, v162, v114
	v_or_b32_e32 v152, 0x120, v152
	v_cvt_pk_bf16_f32 v135, v116, v117
	v_lshl_add_u64 v[136:137], s[34:35], 0, v[152:153]
	global_store_dwordx2 v[136:137], v[134:135], off
	s_waitcnt lgkmcnt(0)
	v_add_f32_e32 v114, v114, v115
	ds_bpermute_b32 v115, v144, v114
	v_lshl_add_u32 v134, v163, 2, v164
	s_and_saveexec_b64 s[40:41], s[36:37]
	s_cbranch_execz .LBB0_102
	s_waitcnt lgkmcnt(0)
	v_add_f32_e32 v114, v114, v115
	ds_write_b32 v134, v114

; __device__ __forceinline__ unsigned cvt_pk(float lo, float hi) { f32x2_t v = {lo, hi}; bf16x2_t b = __builtin_convertvector(v, bf16x2_t); return __builtin_bit_cast(unsigned, b); }
; __device__ __forceinline__ void epi_resid(Acc& acc, int pm, int pn, const float* xsrc, float* xdst, bf16_t* xb, float* ssq, float alpha, LAS unsigned char* lds) {
;     ...
;             f32x4 xs[2][2][2];
; #pragma unroll
;             for (int mm = 0; mm < 2; ++mm)
; #pragma unroll
;                 for (int bj = 0; bj < 2; ++bj)
; #pragma unroll
;                     for (int n = 0; n < 2; ++n) {
;                         const int row = pm * 256 + ai * 128 + t.wr * 64 + (mp * 2 + mm) * 16 + t.fr;
;                         xs[mm][bj][n] = *(const f32x4*)(xsrc + (size_t)row * DM + pn * 256 + bj * 128 + t.wc * 32 + n * 16 + t.fq * 4);
;                     }
; #pragma unroll
;             for (int mm = 0; mm < 2; ++mm) {
;                 const int m = mp * 2 + mm;
;                 const int rl = ai * 128 + t.wr * 64 + m * 16 + t.fr;
;                 const int row = pm * 256 + rl;
;                 float ss = 0.f;
; #pragma unroll
;                 for (int bj = 0; bj < 2; ++bj)
; #pragma unroll
;                     for (int n = 0; n < 2; ++n) {
;                         size_t off = (size_t)row * DM + pn * 256 + bj * 128 + t.wc * 32 + n * 16 + t.fq * 4;
;                         f32x4 v = xs[mm][bj][n] + acc[ai][bj][m][n] * alpha;
;                         *(f32x4*)(xdst + off) = v;
;                         u32x2 w; w[0] = cvt_pk(v[0], v[1]); w[1] = cvt_pk(v[2], v[3]);
;                         *(u32x2*)(xb + off) = w;
;                         ss += v[0] * v[0] + v[1] * v[1] + v[2] * v[2] + v[3] * v[3];
;                     }
;                 ss += __shfl_xor(ss, 16); ss += __shfl_xor(ss, 32);
;                 if (t.fq == 0) red[t.wc * 256 + rl] = ss;
.LBB0_104:
	s_or_b64 exec, exec, s[40:41]
	v_or_b32_e32 v98, 32, v156
	s_waitcnt lgkmcnt(0)
	v_ashrrev_i32_e32 v99, 31, v98
	v_lshlrev_b64 v[98:99], 12, v[98:99]
	v_lshl_add_u64 v[98:99], v[158:159], 0, v[98:99]
	v_mov_b32_e32 v118, v204
	v_mov_b32_e32 v119, v205
	v_mov_b32_e32 v120, v206
	v_mov_b32_e32 v121, v207
	v_mov_b32_e32 v122, v208
	v_mov_b32_e32 v123, v209
	v_mov_b32_e32 v124, v210
	v_mov_b32_e32 v125, v211
	v_mov_b32_e32 v126, v212
	v_mov_b32_e32 v127, v213
	v_mov_b32_e32 v128, v214
	v_mov_b32_e32 v129, v215
	v_mov_b32_e32 v114, v216
	v_mov_b32_e32 v115, v217
	v_mov_b32_e32 v116, v218
	v_mov_b32_e32 v117, v219
	v_or_b32_e32 v98, 48, v156
	v_ashrrev_i32_e32 v99, 31, v98
	v_lshlrev_b64 v[98:99], 12, v[98:99]
	v_lshl_add_u64 v[98:99], v[158:159], 0, v[98:99]
	v_mov_b32_e32 v110, v220
	v_mov_b32_e32 v111, v221
	v_mov_b32_e32 v112, v222
	v_mov_b32_e32 v113, v223
	v_mov_b32_e32 v106, v224
	v_mov_b32_e32 v107, v225
	v_mov_b32_e32 v108, v226
	v_mov_b32_e32 v109, v227
	v_mov_b32_e32 v102, v228
	v_mov_b32_e32 v103, v229
	v_mov_b32_e32 v104, v230
	v_mov_b32_e32 v105, v231
	s_nop 0
	v_mov_b32_e32 v98, v232
	v_mov_b32_e32 v99, v233
	v_mov_b32_e32 v100, v234
	v_mov_b32_e32 v101, v235
	v_add_u32_e32 v188, 0x80, v156
	v_ashrrev_i32_e32 v189, 31, v188
	v_lshlrev_b64 v[188:189], 12, v[188:189]
	v_lshl_add_u64 v[188:189], v[158:159], 0, v[188:189]
	global_load_dwordx4 v[204:207], v[188:189], off
	global_load_dwordx4 v[208:211], v[188:189], off offset:64
	global_load_dwordx4 v[212:215], v[188:189], off offset:512
	global_load_dwordx4 v[216:219], v[188:189], off offset:576
	v_add_u32_e32 v190, 0x90, v156
	v_ashrrev_i32_e32 v191, 31, v190
	v_lshlrev_b64 v[190:191], 12, v[190:191]
	v_lshl_add_u64 v[190:191], v[158:159], 0, v[190:191]
	global_load_dwordx4 v[220:223], v[190:191], off
	global_load_dwordx4 v[224:227], v[190:191], off offset:64
	global_load_dwordx4 v[228:231], v[190:191], off offset:512
	global_load_dwordx4 v[232:235], v[190:191], off offset:576
	v_add3_u32 v130, s13, v163, 32
	v_ashrrev_i32_e32 v131, 31, v130
	v_lshlrev_b64 v[130:131], 10, v[130:131]
	v_lshl_add_u64 v[130:131], v[130:131], 0, v[154:155]
	v_mov_b32_e32 v181, v180
	s_waitcnt lgkmcnt(0)
	v_pk_fma_f32 v[96:97], v[180:181], v[96:97], v[120:121]
	v_pk_fma_f32 v[94:95], v[182:183], v[94:95], v[118:119]
	v_lshl_add_u64 v[118:119], v[130:131], 2, s[20:21]
	v_lshlrev_b64 v[130:131], 1, v[130:131]
	v_cvt_pk_bf16_f32 v120, v94, v95
	v_cvt_pk_bf16_f32 v121, v96, v97
	v_lshl_add_u64 v[132:133], s[34:35], 0, v[130:131]
	global_store_dwordx4 v[118:119], v[94:97], off
	global_store_dwordx2 v[132:133], v[120:121], off
	v_mul_f32_e32 v120, v95, v95
	v_pk_fma_f32 v[92:93], v[180:181], v[92:93], v[124:125]
	v_pk_fma_f32 v[90:91], v[182:183], v[90:91], v[122:123]
	v_fmac_f32_e32 v120, v94, v94
	global_store_dwordx4 v[118:119], v[90:93], off offset:64
	v_cvt_pk_bf16_f32 v94, v90, v91
	v_fmac_f32_e32 v120, v96, v96
	v_mul_f32_e32 v91, v91, v91
	v_fmac_f32_e32 v91, v90, v90
	v_fmac_f32_e32 v120, v97, v97
	v_or_b32_e32 v96, 32, v130
	v_mov_b32_e32 v97, v131
	v_fmac_f32_e32 v91, v92, v92
	v_cvt_pk_bf16_f32 v95, v92, v93
	v_lshl_add_u64 v[96:97], s[34:35], 0, v[96:97]
	v_fmac_f32_e32 v91, v93, v93
	v_pk_fma_f32 v[88:89], v[180:181], v[88:89], v[128:129]
	v_pk_fma_f32 v[86:87], v[182:183], v[86:87], v[126:127]
	v_or_b32_e32 v92, 0x100, v130
	v_mov_b32_e32 v93, v131
	global_store_dwordx2 v[96:97], v[94:95], off
	v_add_f32_e32 v94, v120, v91
	global_store_dwordx4 v[118:119], v[86:89], off offset:512
	v_cvt_pk_bf16_f32 v90, v86, v87
	v_cvt_pk_bf16_f32 v91, v88, v89
	v_lshl_add_u64 v[92:93], s[34:35], 0, v[92:93]
	v_mul_f32_e32 v87, v87, v87
	v_pk_fma_f32 v[84:85], v[180:181], v[84:85], v[116:117]
	v_pk_fma_f32 v[82:83], v[182:183], v[82:83], v[114:115]
	global_store_dwordx2 v[92:93], v[90:91], off
	v_fmac_f32_e32 v87, v86, v86
	global_store_dwordx4 v[118:119], v[82:85], off offset:576
	v_cvt_pk_bf16_f32 v86, v82, v83
	v_fmac_f32_e32 v87, v88, v88
	v_mul_f32_e32 v83, v83, v83
	v_fmac_f32_e32 v83, v82, v82
	v_fmac_f32_e32 v87, v89, v89
	v_fmac_f32_e32 v83, v84, v84
	v_add_f32_e32 v90, v94, v87
	v_fmac_f32_e32 v83, v85, v85
	v_add_f32_e32 v82, v90, v83
	ds_bpermute_b32 v83, v162, v82
	v_or_b32_e32 v130, 0x120, v130
	v_cvt_pk_bf16_f32 v87, v84, v85
	v_lshl_add_u64 v[88:89], s[34:35], 0, v[130:131]
	global_store_dwordx2 v[88:89], v[86:87], off
	s_waitcnt lgkmcnt(0)
	v_add_f32_e32 v82, v82, v83
	ds_bpermute_b32 v83, v144, v82
	s_and_saveexec_b64 s[40:41], s[36:37]
	s_mov_b64 s[80:81], s[4:5]
	s_cbranch_execz .LBB0_106
	s_waitcnt lgkmcnt(0)
	v_add_f32_e32 v82, v82, v83
	ds_write_b32 v134, v82 offset:128

; __device__ __forceinline__ unsigned cvt_pk(float lo, float hi) { f32x2_t v = {lo, hi}; bf16x2_t b = __builtin_convertvector(v, bf16x2_t); return __builtin_bit_cast(unsigned, b); }
; __device__ __forceinline__ void epi_resid(Acc& acc, int pm, int pn, const float* xsrc, float* xdst, bf16_t* xb, float* ssq, float alpha, LAS unsigned char* lds) {
;     ...
;             f32x4 xs[2][2][2];
; #pragma unroll
;             for (int mm = 0; mm < 2; ++mm)
; #pragma unroll
;                 for (int bj = 0; bj < 2; ++bj)
; #pragma unroll
;                     for (int n = 0; n < 2; ++n) {
;                         const int row = pm * 256 + ai * 128 + t.wr * 64 + (mp * 2 + mm) * 16 + t.fr;
;                         xs[mm][bj][n] = *(const f32x4*)(xsrc + (size_t)row * DM + pn * 256 + bj * 128 + t.wc * 32 + n * 16 + t.fq * 4);
;                     }
; #pragma unroll
;             for (int mm = 0; mm < 2; ++mm) {
;                 const int m = mp * 2 + mm;
;                 const int rl = ai * 128 + t.wr * 64 + m * 16 + t.fr;
;                 const int row = pm * 256 + rl;
;                 float ss = 0.f;
; #pragma unroll
;                 for (int bj = 0; bj < 2; ++bj)
; #pragma unroll
;                     for (int n = 0; n < 2; ++n) {
;                         size_t off = (size_t)row * DM + pn * 256 + bj * 128 + t.wc * 32 + n * 16 + t.fq * 4;
;                         f32x4 v = xs[mm][bj][n] + acc[ai][bj][m][n] * alpha;
;                         *(f32x4*)(xdst + off) = v;
;                         u32x2 w; w[0] = cvt_pk(v[0], v[1]); w[1] = cvt_pk(v[2], v[3]);
;                         *(u32x2*)(xb + off) = w;
;                         ss += v[0] * v[0] + v[1] * v[1] + v[2] * v[2] + v[3] * v[3];
;                     }
;                 ss += __shfl_xor(ss, 16); ss += __shfl_xor(ss, 32);
;                 if (t.fq == 0) red[t.wc * 256 + rl] = ss;
.LBB0_108:
	s_or_b64 exec, exec, s[40:41]
	s_waitcnt lgkmcnt(0)
	v_lshlrev_b64 v[66:67], 12, v[156:157]
	v_lshl_add_u64 v[66:67], v[158:159], 0, v[66:67]
	s_mov_b64 s[40:41], 0x80000
	v_lshl_add_u64 v[68:69], v[66:67], 0, s[40:41]
	v_add_co_u32_e32 v66, vcc, 0x80000, v66
	v_add_u32_e32 v86, 0x90, v156
	s_nop 0
	v_addc_co_u32_e32 v67, vcc, 0, v67, vcc
	s_waitcnt vmcnt(0)
	v_mov_b32_e32 v88, v204
	v_mov_b32_e32 v89, v205
	v_mov_b32_e32 v90, v206
	v_mov_b32_e32 v91, v207
	v_mov_b32_e32 v92, v208
	v_mov_b32_e32 v93, v209
	v_mov_b32_e32 v94, v210
	v_mov_b32_e32 v95, v211
	v_mov_b32_e32 v96, v212
	v_mov_b32_e32 v97, v213
	v_mov_b32_e32 v98, v214
	v_mov_b32_e32 v99, v215
	v_mov_b32_e32 v82, v216
	v_mov_b32_e32 v83, v217
	v_mov_b32_e32 v84, v218
	v_mov_b32_e32 v85, v219
	v_ashrrev_i32_e32 v87, 31, v86
	v_lshlrev_b64 v[66:67], 12, v[86:87]
	v_lshl_add_u64 v[66:67], v[158:159], 0, v[66:67]
	v_mov_b32_e32 v78, v220
	v_mov_b32_e32 v79, v221
	v_mov_b32_e32 v80, v222
	v_mov_b32_e32 v81, v223
	v_mov_b32_e32 v74, v224
	v_mov_b32_e32 v75, v225
	v_mov_b32_e32 v76, v226
	v_mov_b32_e32 v77, v227
	v_mov_b32_e32 v70, v228
	v_mov_b32_e32 v71, v229
	v_mov_b32_e32 v72, v230
	v_mov_b32_e32 v73, v231
	s_nop 0
	v_mov_b32_e32 v66, v232
	v_mov_b32_e32 v67, v233
	v_mov_b32_e32 v68, v234
	v_mov_b32_e32 v69, v235
	v_add_u32_e32 v188, 0xa0, v156
	v_ashrrev_i32_e32 v189, 31, v188
	v_lshlrev_b64 v[188:189], 12, v[188:189]
	v_lshl_add_u64 v[188:189], v[158:159], 0, v[188:189]
	global_load_dwordx4 v[204:207], v[188:189], off
	global_load_dwordx4 v[208:211], v[188:189], off offset:64
	global_load_dwordx4 v[212:215], v[188:189], off offset:512
	global_load_dwordx4 v[216:219], v[188:189], off offset:576
	v_add_u32_e32 v190, 0xb0, v156
	v_ashrrev_i32_e32 v191, 31, v190
	v_lshlrev_b64 v[190:191], 12, v[190:191]
	v_lshl_add_u64 v[190:191], v[158:159], 0, v[190:191]
	global_load_dwordx4 v[220:223], v[190:191], off
	global_load_dwordx4 v[224:227], v[190:191], off offset:64
	global_load_dwordx4 v[228:231], v[190:191], off offset:512
	global_load_dwordx4 v[232:235], v[190:191], off offset:576
	v_add_u32_e32 v100, 0x80, v160
	v_ashrrev_i32_e32 v101, 31, v100
	v_lshlrev_b64 v[100:101], 10, v[100:101]
	v_lshl_add_u64 v[100:101], v[100:101], 0, v[154:155]
	v_mov_b32_e32 v181, v180
	s_waitcnt lgkmcnt(0)
	v_pk_fma_f32 v[64:65], v[180:181], v[64:65], v[90:91]
	v_pk_fma_f32 v[62:63], v[182:183], v[62:63], v[88:89]
	v_lshl_add_u64 v[88:89], v[100:101], 2, s[20:21]
	v_lshlrev_b64 v[100:101], 1, v[100:101]
	v_cvt_pk_bf16_f32 v90, v62, v63
	v_cvt_pk_bf16_f32 v91, v64, v65
	v_lshl_add_u64 v[102:103], s[34:35], 0, v[100:101]
	global_store_dwordx4 v[88:89], v[62:65], off
	global_store_dwordx2 v[102:103], v[90:91], off
	v_mul_f32_e32 v90, v63, v63
	v_pk_fma_f32 v[60:61], v[180:181], v[60:61], v[94:95]
	v_pk_fma_f32 v[58:59], v[182:183], v[58:59], v[92:93]
	v_fmac_f32_e32 v90, v62, v62
	global_store_dwordx4 v[88:89], v[58:61], off offset:64
	v_cvt_pk_bf16_f32 v62, v58, v59
	v_fmac_f32_e32 v90, v64, v64
	v_mul_f32_e32 v59, v59, v59
	v_fmac_f32_e32 v59, v58, v58
	v_fmac_f32_e32 v90, v65, v65
	v_or_b32_e32 v64, 32, v100
	v_mov_b32_e32 v65, v101
	v_fmac_f32_e32 v59, v60, v60
	v_cvt_pk_bf16_f32 v63, v60, v61
	v_lshl_add_u64 v[64:65], s[34:35], 0, v[64:65]
	v_fmac_f32_e32 v59, v61, v61
	v_pk_fma_f32 v[56:57], v[180:181], v[56:57], v[98:99]
	v_pk_fma_f32 v[54:55], v[182:183], v[54:55], v[96:97]
	v_or_b32_e32 v60, 0x100, v100
	v_mov_b32_e32 v61, v101
	global_store_dwordx2 v[64:65], v[62:63], off
	v_add_f32_e32 v62, v90, v59
	global_store_dwordx4 v[88:89], v[54:57], off offset:512
	v_cvt_pk_bf16_f32 v58, v54, v55
	v_cvt_pk_bf16_f32 v59, v56, v57
	v_lshl_add_u64 v[60:61], s[34:35], 0, v[60:61]
	v_mul_f32_e32 v55, v55, v55
	v_pk_fma_f32 v[52:53], v[180:181], v[52:53], v[84:85]
	v_pk_fma_f32 v[50:51], v[182:183], v[50:51], v[82:83]
	global_store_dwordx2 v[60:61], v[58:59], off
	v_fmac_f32_e32 v55, v54, v54
	global_store_dwordx4 v[88:89], v[50:53], off offset:576
	v_cvt_pk_bf16_f32 v54, v50, v51
	v_fmac_f32_e32 v55, v56, v56
	v_mul_f32_e32 v51, v51, v51
	v_fmac_f32_e32 v51, v50, v50
	v_fmac_f32_e32 v55, v57, v57
	v_fmac_f32_e32 v51, v52, v52
	v_add_f32_e32 v58, v62, v55
	v_fmac_f32_e32 v51, v53, v53
	v_add_f32_e32 v50, v58, v51
	ds_bpermute_b32 v51, v162, v50
	v_or_b32_e32 v100, 0x120, v100
	v_cvt_pk_bf16_f32 v55, v52, v53
	v_lshl_add_u64 v[56:57], s[34:35], 0, v[100:101]
	global_store_dwordx2 v[56:57], v[54:55], off
	s_waitcnt lgkmcnt(0)
	v_add_f32_e32 v50, v50, v51
	ds_bpermute_b32 v51, v144, v50
	s_and_saveexec_b64 s[40:41], s[36:37]
	s_cbranch_execz .LBB0_110
	s_waitcnt lgkmcnt(0)
	v_add_f32_e32 v50, v50, v51
	ds_write_b32 v134, v50 offset:512

; __device__ __forceinline__ unsigned cvt_pk(float lo, float hi) { f32x2_t v = {lo, hi}; bf16x2_t b = __builtin_convertvector(v, bf16x2_t); return __builtin_bit_cast(unsigned, b); }
; __device__ __forceinline__ void epi_resid(Acc& acc, int pm, int pn, const float* xsrc, float* xdst, bf16_t* xb, float* ssq, float alpha, LAS unsigned char* lds) {
;     ...
;             f32x4 xs[2][2][2];
; #pragma unroll
;             for (int mm = 0; mm < 2; ++mm)
; #pragma unroll
;                 for (int bj = 0; bj < 2; ++bj)
; #pragma unroll
;                     for (int n = 0; n < 2; ++n) {
;                         const int row = pm * 256 + ai * 128 + t.wr * 64 + (mp * 2 + mm) * 16 + t.fr;
;                         xs[mm][bj][n] = *(const f32x4*)(xsrc + (size_t)row * DM + pn * 256 + bj * 128 + t.wc * 32 + n * 16 + t.fq * 4);
;                     }
; #pragma unroll
;             for (int mm = 0; mm < 2; ++mm) {
;                 const int m = mp * 2 + mm;
;                 const int rl = ai * 128 + t.wr * 64 + m * 16 + t.fr;
;                 const int row = pm * 256 + rl;
;                 float ss = 0.f;
; #pragma unroll
;                 for (int bj = 0; bj < 2; ++bj)
; #pragma unroll
;                     for (int n = 0; n < 2; ++n) {
;                         size_t off = (size_t)row * DM + pn * 256 + bj * 128 + t.wc * 32 + n * 16 + t.fq * 4;
;                         f32x4 v = xs[mm][bj][n] + acc[ai][bj][m][n] * alpha;
;                         *(f32x4*)(xdst + off) = v;
;                         u32x2 w; w[0] = cvt_pk(v[0], v[1]); w[1] = cvt_pk(v[2], v[3]);
;                         *(u32x2*)(xb + off) = w;
;                         ss += v[0] * v[0] + v[1] * v[1] + v[2] * v[2] + v[3] * v[3];
;                     }
;                 ss += __shfl_xor(ss, 16); ss += __shfl_xor(ss, 32);
;                 if (t.fq == 0) red[t.wc * 256 + rl] = ss;
.LBB0_112:
	s_or_b64 exec, exec, s[40:41]
	s_waitcnt lgkmcnt(0)
	v_lshlrev_b64 v[34:35], 12, v[156:157]
	v_lshl_add_u64 v[34:35], v[158:159], 0, v[34:35]
	s_mov_b64 s[40:41], 0xa0000
	v_lshl_add_u64 v[36:37], v[34:35], 0, s[40:41]
	v_add_co_u32_e32 v34, vcc, 0xa0000, v34
	v_add_u32_e32 v54, 0xb0, v156
	s_nop 0
	v_addc_co_u32_e32 v35, vcc, 0, v35, vcc
	s_waitcnt vmcnt(0)
	v_mov_b32_e32 v56, v204
	v_mov_b32_e32 v57, v205
	v_mov_b32_e32 v58, v206
	v_mov_b32_e32 v59, v207
	v_mov_b32_e32 v60, v208
	v_mov_b32_e32 v61, v209
	v_mov_b32_e32 v62, v210
	v_mov_b32_e32 v63, v211
	v_mov_b32_e32 v64, v212
	v_mov_b32_e32 v65, v213
	v_mov_b32_e32 v66, v214
	v_mov_b32_e32 v67, v215
	v_mov_b32_e32 v50, v216
	v_mov_b32_e32 v51, v217
	v_mov_b32_e32 v52, v218
	v_mov_b32_e32 v53, v219
	v_ashrrev_i32_e32 v55, 31, v54
	v_lshlrev_b64 v[34:35], 12, v[54:55]
	v_lshl_add_u64 v[34:35], v[158:159], 0, v[34:35]
	v_mov_b32_e32 v46, v220
	v_mov_b32_e32 v47, v221
	v_mov_b32_e32 v48, v222
	v_mov_b32_e32 v49, v223
	v_mov_b32_e32 v42, v224
	v_mov_b32_e32 v43, v225
	v_mov_b32_e32 v44, v226
	v_mov_b32_e32 v45, v227
	v_mov_b32_e32 v38, v228
	v_mov_b32_e32 v39, v229
	v_mov_b32_e32 v40, v230
	v_mov_b32_e32 v41, v231
	s_nop 0
	v_mov_b32_e32 v34, v232
	v_mov_b32_e32 v35, v233
	v_mov_b32_e32 v36, v234
	v_mov_b32_e32 v37, v235
	v_add_u32_e32 v68, 0xa0, v160
	v_ashrrev_i32_e32 v69, 31, v68
	v_lshlrev_b64 v[68:69], 10, v[68:69]
	v_lshl_add_u64 v[68:69], v[68:69], 0, v[154:155]
	v_mov_b32_e32 v181, v180
	s_waitcnt lgkmcnt(0)
	v_pk_fma_f32 v[32:33], v[180:181], v[32:33], v[58:59]
	v_pk_fma_f32 v[30:31], v[182:183], v[30:31], v[56:57]
	v_lshl_add_u64 v[56:57], v[68:69], 2, s[20:21]
	v_lshlrev_b64 v[68:69], 1, v[68:69]
	v_cvt_pk_bf16_f32 v58, v30, v31
	v_cvt_pk_bf16_f32 v59, v32, v33
	v_lshl_add_u64 v[70:71], s[34:35], 0, v[68:69]
	global_store_dwordx4 v[56:57], v[30:33], off
	global_store_dwordx2 v[70:71], v[58:59], off
	v_mul_f32_e32 v58, v31, v31
	v_pk_fma_f32 v[28:29], v[180:181], v[28:29], v[62:63]
	v_pk_fma_f32 v[26:27], v[182:183], v[26:27], v[60:61]
	v_fmac_f32_e32 v58, v30, v30
	global_store_dwordx4 v[56:57], v[26:29], off offset:64
	v_cvt_pk_bf16_f32 v30, v26, v27
	v_fmac_f32_e32 v58, v32, v32
	v_mul_f32_e32 v27, v27, v27
	v_fmac_f32_e32 v27, v26, v26
	v_fmac_f32_e32 v58, v33, v33
	v_or_b32_e32 v32, 32, v68
	v_mov_b32_e32 v33, v69
	v_fmac_f32_e32 v27, v28, v28
	v_cvt_pk_bf16_f32 v31, v28, v29
	v_lshl_add_u64 v[32:33], s[34:35], 0, v[32:33]
	v_fmac_f32_e32 v27, v29, v29
	v_pk_fma_f32 v[24:25], v[180:181], v[24:25], v[66:67]
	v_pk_fma_f32 v[22:23], v[182:183], v[22:23], v[64:65]
	v_or_b32_e32 v28, 0x100, v68
	v_mov_b32_e32 v29, v69
	global_store_dwordx2 v[32:33], v[30:31], off
	v_add_f32_e32 v30, v58, v27
	global_store_dwordx4 v[56:57], v[22:25], off offset:512
	v_cvt_pk_bf16_f32 v26, v22, v23
	v_cvt_pk_bf16_f32 v27, v24, v25
	v_lshl_add_u64 v[28:29], s[34:35], 0, v[28:29]
	v_mul_f32_e32 v23, v23, v23
	v_pk_fma_f32 v[20:21], v[180:181], v[20:21], v[52:53]
	v_pk_fma_f32 v[18:19], v[182:183], v[18:19], v[50:51]
	global_store_dwordx2 v[28:29], v[26:27], off
	v_fmac_f32_e32 v23, v22, v22
	global_store_dwordx4 v[56:57], v[18:21], off offset:576
	v_cvt_pk_bf16_f32 v22, v18, v19
	v_fmac_f32_e32 v23, v24, v24
	v_mul_f32_e32 v19, v19, v19
	v_fmac_f32_e32 v19, v18, v18
	v_fmac_f32_e32 v23, v25, v25
	v_fmac_f32_e32 v19, v20, v20
	v_add_f32_e32 v26, v30, v23
	v_fmac_f32_e32 v19, v21, v21
	v_add_f32_e32 v18, v26, v19
	ds_bpermute_b32 v19, v162, v18
	v_or_b32_e32 v68, 0x120, v68
	v_cvt_pk_bf16_f32 v23, v20, v21
	v_lshl_add_u64 v[24:25], s[34:35], 0, v[68:69]
	global_store_dwordx2 v[24:25], v[22:23], off
	s_waitcnt lgkmcnt(0)
	v_add_f32_e32 v18, v18, v19
	ds_bpermute_b32 v19, v144, v18
	s_and_saveexec_b64 s[40:41], s[36:37]
	s_cbranch_execz .LBB0_114
	s_waitcnt lgkmcnt(0)
	v_add_f32_e32 v18, v18, v19
	ds_write_b32 v134, v18 offset:640
